# stacked on the early-store version: attention output-stage gain loads hoisted before the stores, Q-fragment loads issued up front (layer 0)
# speedup vs baseline: 1.0005x; 1.0005x over previous
.LBB0_208:
	s_or_b64 exec, exec, s[16:17]
	v_mov_b32_e32 v1, s3
	s_waitcnt lgkmcnt(0)
	s_barrier
	ds_read_b32 v1, v1
	s_movk_i32 s0, 0x107
	s_mov_b64 s[16:17], -1
	s_waitcnt lgkmcnt(0)
	s_barrier
	v_cmp_lt_i32_e32 vcc, s0, v1
	v_readfirstlane_b32 s18, v1
	s_cbranch_vccnz .LBB0_203
	s_cmp_gt_i32 s18, 7
	s_cbranch_scc0 .LBB0_243
	s_add_i32 s0, s18, -8
	s_lshr_b32 s61, s0, 5
	s_andn2_b32 s62, 31, s0
	s_sub_i32 s0, 15, s61
	s_lshl_b32 s0, s0, 2
	s_add_i32 s0, s0, 0
	s_add_i32 s0, s0, 0x20040
	v_mov_b32_e32 v1, s0
	v_readfirstlane_b32 s0, v160
	s_lshr_b32 s16, s0, 1
	s_lshl_b32 s33, s62, 7
	s_and_b32 s19, s16, 0x60
	s_or_b32 s70, s19, s33
	v_or_b32_e32 v2, s70, v211
	s_lshl_b32 s16, s61, 7
	v_lshlrev_b32_e32 v2, 11, v2
	v_mov_b32_e32 v3, v0
	s_sub_i32 s60, 0x380, s16
	s_lshr_b32 s1, s0, 8
	v_lshl_add_u64 v[2:3], s[24:25], 0, v[2:3]
	s_lshl_b32 s20, s60, 1
	v_lshl_add_u64 v[170:171], v[2:3], 0, s[20:21]
	s_lshl_b32 s16, s1, 7
	s_mov_b32 s17, s21
	v_lshl_add_u64 v[2:3], v[170:171], 0, s[16:17]
	v_mov_b32_e32 v167, v0
	v_lshl_add_u64 v[2:3], v[2:3], 0, v[166:167]
	global_load_dwordx4 v[4:7], v[2:3], off
	global_load_dwordx4 v[116:119], v[2:3], off offset:32
	global_load_dwordx4 v[120:123], v[2:3], off offset:64
	global_load_dwordx4 v[124:127], v[2:3], off offset:96
	ds_read_b32 v1, v1
	s_waitcnt vmcnt(0)
	v_lshlrev_b32_e32 v8, 16, v4
	v_and_b32_e32 v9, 0xffff0000, v4
	v_lshlrev_b32_e32 v4, 16, v5
	v_and_b32_e32 v5, 0xffff0000, v5
	v_pk_mul_f32 v[4:5], v[4:5], s[26:27] op_sel_hi:[1,0]
	v_pk_mul_f32 v[8:9], v[8:9], s[26:27] op_sel_hi:[1,0]
	v_cvt_pk_bf16_f32 v113, v4, v5
	v_lshlrev_b32_e32 v4, 16, v6
	v_and_b32_e32 v5, 0xffff0000, v6
	v_pk_mul_f32 v[4:5], v[4:5], s[26:27] op_sel_hi:[1,0]
	v_cvt_pk_bf16_f32 v112, v8, v9
	v_cvt_pk_bf16_f32 v114, v4, v5
	v_lshlrev_b32_e32 v4, 16, v7
	v_and_b32_e32 v5, 0xffff0000, v7
	v_pk_mul_f32 v[4:5], v[4:5], s[26:27] op_sel_hi:[1,0]
	s_nop 0
	v_cvt_pk_bf16_f32 v115, v4, v5
	v_lshlrev_b32_e32 v8, 16, v116
	v_and_b32_e32 v9, 0xffff0000, v116
	v_lshlrev_b32_e32 v4, 16, v117
	v_and_b32_e32 v5, 0xffff0000, v117
	v_pk_mul_f32 v[4:5], v[4:5], s[26:27] op_sel_hi:[1,0]
	v_pk_mul_f32 v[8:9], v[8:9], s[26:27] op_sel_hi:[1,0]
	v_cvt_pk_bf16_f32 v117, v4, v5
	v_lshlrev_b32_e32 v4, 16, v118
	v_and_b32_e32 v5, 0xffff0000, v118
	v_pk_mul_f32 v[4:5], v[4:5], s[26:27] op_sel_hi:[1,0]
	v_cvt_pk_bf16_f32 v116, v8, v9
	v_cvt_pk_bf16_f32 v118, v4, v5
	v_lshlrev_b32_e32 v4, 16, v119
	v_and_b32_e32 v5, 0xffff0000, v119
	v_pk_mul_f32 v[4:5], v[4:5], s[26:27] op_sel_hi:[1,0]
	s_nop 0
	v_cvt_pk_bf16_f32 v119, v4, v5
	v_lshlrev_b32_e32 v8, 16, v120
	v_and_b32_e32 v9, 0xffff0000, v120
	v_lshlrev_b32_e32 v4, 16, v121
	v_and_b32_e32 v5, 0xffff0000, v121
	v_pk_mul_f32 v[4:5], v[4:5], s[26:27] op_sel_hi:[1,0]
	v_pk_mul_f32 v[8:9], v[8:9], s[26:27] op_sel_hi:[1,0]
	v_cvt_pk_bf16_f32 v121, v4, v5
	v_lshlrev_b32_e32 v4, 16, v122
	v_and_b32_e32 v5, 0xffff0000, v122
	v_pk_mul_f32 v[4:5], v[4:5], s[26:27] op_sel_hi:[1,0]
	v_cvt_pk_bf16_f32 v120, v8, v9
	v_cvt_pk_bf16_f32 v122, v4, v5
	v_lshlrev_b32_e32 v4, 16, v123
	v_and_b32_e32 v5, 0xffff0000, v123
	v_pk_mul_f32 v[4:5], v[4:5], s[26:27] op_sel_hi:[1,0]
	s_nop 0
	v_cvt_pk_bf16_f32 v123, v4, v5
	v_lshlrev_b32_e32 v6, 16, v124
	v_and_b32_e32 v7, 0xffff0000, v124
	v_lshlrev_b32_e32 v2, 16, v125
	v_and_b32_e32 v3, 0xffff0000, v125
	v_pk_mul_f32 v[2:3], v[2:3], s[26:27] op_sel_hi:[1,0]
	v_pk_mul_f32 v[6:7], v[6:7], s[26:27] op_sel_hi:[1,0]
	v_cvt_pk_bf16_f32 v125, v2, v3
	v_lshlrev_b32_e32 v2, 16, v126
	v_and_b32_e32 v3, 0xffff0000, v126
	v_pk_mul_f32 v[2:3], v[2:3], s[26:27] op_sel_hi:[1,0]
	v_and_b32_e32 v4, 0xffff0000, v116
	v_cvt_pk_bf16_f32 v126, v2, v3
	v_lshlrev_b32_e32 v2, 16, v127
	v_and_b32_e32 v3, 0xffff0000, v127
	v_pk_mul_f32 v[2:3], v[2:3], s[26:27] op_sel_hi:[1,0]
	v_mul_f32_e32 v4, v4, v4
	v_cvt_pk_bf16_f32 v127, v2, v3
	v_and_b32_e32 v3, 0xffff0000, v112
	v_lshlrev_b32_e32 v2, 16, v112
	v_mul_f32_e32 v3, v3, v3
	v_fmac_f32_e32 v3, v2, v2
	v_lshlrev_b32_e32 v2, 16, v113
	v_fmac_f32_e32 v3, v2, v2
	v_and_b32_e32 v2, 0xffff0000, v113
	v_fmac_f32_e32 v3, v2, v2
	v_lshlrev_b32_e32 v2, 16, v114
	v_fmac_f32_e32 v3, v2, v2
	v_and_b32_e32 v2, 0xffff0000, v114
	v_fmac_f32_e32 v3, v2, v2
	v_lshlrev_b32_e32 v2, 16, v115
	v_fmac_f32_e32 v3, v2, v2
	v_and_b32_e32 v2, 0xffff0000, v115
	v_fmac_f32_e32 v3, v2, v2
	v_lshlrev_b32_e32 v2, 16, v116
	v_fmac_f32_e32 v4, v2, v2
	v_lshlrev_b32_e32 v2, 16, v117
	v_fmac_f32_e32 v4, v2, v2
	v_and_b32_e32 v2, 0xffff0000, v117
	v_fmac_f32_e32 v4, v2, v2
	v_lshlrev_b32_e32 v2, 16, v118
	v_fmac_f32_e32 v4, v2, v2
	v_and_b32_e32 v2, 0xffff0000, v118
	v_fmac_f32_e32 v4, v2, v2
	v_lshlrev_b32_e32 v2, 16, v119
	v_fmac_f32_e32 v4, v2, v2
	v_and_b32_e32 v2, 0xffff0000, v119
	v_fmac_f32_e32 v4, v2, v2
	v_add_f32_e32 v2, v3, v4
	v_and_b32_e32 v4, 0xffff0000, v120
	v_lshlrev_b32_e32 v3, 16, v120
	v_mul_f32_e32 v4, v4, v4
	v_fmac_f32_e32 v4, v3, v3
	v_lshlrev_b32_e32 v3, 16, v121
	v_fmac_f32_e32 v4, v3, v3
	v_and_b32_e32 v3, 0xffff0000, v121
	v_fmac_f32_e32 v4, v3, v3
	v_lshlrev_b32_e32 v3, 16, v122
	v_fmac_f32_e32 v4, v3, v3
	v_and_b32_e32 v3, 0xffff0000, v122
	v_fmac_f32_e32 v4, v3, v3
	v_lshlrev_b32_e32 v3, 16, v123
	v_fmac_f32_e32 v4, v3, v3
	v_and_b32_e32 v3, 0xffff0000, v123
	v_cvt_pk_bf16_f32 v124, v6, v7
	v_fmac_f32_e32 v4, v3, v3
	v_add_f32_e32 v2, v2, v4
	v_and_b32_e32 v4, 0xffff0000, v124
	v_lshlrev_b32_e32 v3, 16, v124
	v_mul_f32_e32 v4, v4, v4
	v_fmac_f32_e32 v4, v3, v3
	v_lshlrev_b32_e32 v3, 16, v125
	v_fmac_f32_e32 v4, v3, v3
	v_and_b32_e32 v3, 0xffff0000, v125
	v_fmac_f32_e32 v4, v3, v3
	v_lshlrev_b32_e32 v3, 16, v126
	v_fmac_f32_e32 v4, v3, v3
	v_and_b32_e32 v3, 0xffff0000, v126
	v_fmac_f32_e32 v4, v3, v3
	v_lshlrev_b32_e32 v3, 16, v127
	v_fmac_f32_e32 v4, v3, v3
	v_and_b32_e32 v3, 0xffff0000, v127
	v_fmac_f32_e32 v4, v3, v3
	v_add_f32_e32 v2, v2, v4
	v_and_b32_e32 v4, 64, v221
	v_xor_b32_e32 v3, 32, v221
	v_add_u32_e32 v4, 64, v4
	v_cmp_lt_i32_e32 vcc, v3, v4
	s_nop 1
	v_cndmask_b32_e32 v3, v221, v3, vcc
	v_lshlrev_b32_e32 v167, 2, v3
	ds_bpermute_b32 v3, v167, v2
	s_waitcnt lgkmcnt(0)
	v_add_f32_e32 v2, v2, v3
	v_xor_b32_e32 v3, 1, v221
	v_cmp_lt_i32_e32 vcc, v3, v4
	s_nop 1
	v_cndmask_b32_e32 v3, v221, v3, vcc
	v_lshlrev_b32_e32 v3, 2, v3
	ds_bpermute_b32 v3, v3, v2
	s_waitcnt lgkmcnt(0)
	v_max_f32_e32 v3, v3, v3
	v_max_f32_e32 v2, v2, v3
	v_xor_b32_e32 v3, 2, v221
	v_cmp_lt_i32_e32 vcc, v3, v4
	s_nop 1
	v_cndmask_b32_e32 v3, v221, v3, vcc
	v_lshlrev_b32_e32 v3, 2, v3
	ds_bpermute_b32 v3, v3, v2
	s_waitcnt lgkmcnt(0)
	v_max_f32_e32 v3, v3, v3
	v_max_f32_e32 v2, v2, v3
	v_xor_b32_e32 v3, 4, v221
	v_cmp_lt_i32_e32 vcc, v3, v4
	s_nop 1
	v_cndmask_b32_e32 v3, v221, v3, vcc
	v_lshlrev_b32_e32 v3, 2, v3
	ds_bpermute_b32 v3, v3, v2
	s_waitcnt lgkmcnt(0)
	v_max_f32_e32 v3, v3, v3
	v_max_f32_e32 v2, v2, v3
	v_xor_b32_e32 v3, 8, v221
	v_cmp_lt_i32_e32 vcc, v3, v4
	s_nop 1
	v_cndmask_b32_e32 v3, v221, v3, vcc
	v_lshlrev_b32_e32 v3, 2, v3
	ds_bpermute_b32 v3, v3, v2
	s_waitcnt lgkmcnt(0)
	v_max_f32_e32 v3, v3, v3
	v_max_f32_e32 v2, v2, v3
	v_xor_b32_e32 v3, 16, v221
	v_cmp_lt_i32_e32 vcc, v3, v4
	s_nop 1
	v_cndmask_b32_e32 v3, v221, v3, vcc
	v_lshlrev_b32_e32 v3, 2, v3
	ds_bpermute_b32 v3, v3, v2
	s_and_saveexec_b64 s[16:17], s[4:5]
	s_cbranch_execz .LBB0_212
	s_lshr_b32 s63, s0, 6
	s_lshl_b32 s63, s63, 2
	s_add_i32 s63, s63, 0
	s_add_i32 s63, s63, 0x20100
	s_waitcnt lgkmcnt(0)
	v_max_f32_e32 v3, v3, v3
	v_max_f32_e32 v2, v2, v2
	v_max_f32_e32 v2, v2, v3
	v_mov_b32_e32 v3, s63
	ds_write_b32 v3, v2

.LBB0_240:
	s_cmpk_gt_u32 s0, 0xff
	s_waitcnt lgkmcnt(0)
	s_barrier
	s_cbranch_scc1 .LBB0_242
	ds_read_b128 v[10:13], v1
	ds_read_b128 v[80:83], v1 offset:32
	ds_read_b128 v[84:87], v1 offset:64
	ds_read_b128 v[88:91], v1 offset:96
	ds_read_b128 v[92:95], v1 offset:128
	ds_read_b128 v[96:99], v1 offset:160
	ds_read_b128 v[100:103], v1 offset:192
	ds_read_b128 v[104:107], v1 offset:224
	ds_read_b128 v[108:111], v1 offset:256
	ds_read_b128 v[112:115], v1 offset:288
	ds_read_b128 v[116:119], v1 offset:448
	ds_read_b128 v[120:123], v1 offset:320
	ds_read_b128 v[124:127], v1 offset:352
	ds_read_b128 v[2:5], v1 offset:480
	s_waitcnt vmcnt(3)
	ds_read_b128 v[128:131], v1 offset:384
	s_waitcnt vmcnt(2)
	ds_read_b128 v[132:135], v1 offset:416
	s_waitcnt lgkmcnt(5)
	v_pk_fma_f32 v[6:7], v[26:27], v[8:9], v[118:119] op_sel_hi:[1,0,1] neg_lo:[0,0,1] neg_hi:[0,0,1]
	v_pk_fma_f32 v[64:65], v[64:65], v[8:9], v[10:11] op_sel_hi:[1,0,1] neg_lo:[0,0,1] neg_hi:[0,0,1]
	s_waitcnt lgkmcnt(2)
	v_pk_fma_f32 v[2:3], v[28:29], v[8:9], v[2:3] op_sel_hi:[1,0,1] neg_lo:[0,0,1] neg_hi:[0,0,1]
	global_load_dwordx4 v[26:29], v[152:153], off
	v_pk_fma_f32 v[66:67], v[66:67], v[8:9], v[12:13] op_sel_hi:[1,0,1] neg_lo:[0,0,1] neg_hi:[0,0,1]
	s_waitcnt vmcnt(1)
	v_pk_mul_f32 v[140:141], v[64:65], v[64:65]
	v_pk_mul_f32 v[138:139], v[66:67], v[66:67]
	v_add_f32_e32 v1, v140, v141
	v_pk_fma_f32 v[68:69], v[68:69], v[8:9], v[80:81] op_sel_hi:[1,0,1] neg_lo:[0,0,1] neg_hi:[0,0,1]
	v_add_f32_e32 v1, v138, v1
	v_pk_mul_f32 v[80:81], v[68:69], v[68:69]
	v_add_f32_e32 v1, v139, v1
	v_pk_fma_f32 v[70:71], v[70:71], v[8:9], v[82:83] op_sel_hi:[1,0,1] neg_lo:[0,0,1] neg_hi:[0,0,1]
	v_add_f32_e32 v1, v80, v1
	v_pk_mul_f32 v[82:83], v[70:71], v[70:71]
	v_add_f32_e32 v1, v81, v1
	v_pk_fma_f32 v[72:73], v[72:73], v[8:9], v[84:85] op_sel_hi:[1,0,1] neg_lo:[0,0,1] neg_hi:[0,0,1]
	v_add_f32_e32 v1, v82, v1
	v_pk_mul_f32 v[84:85], v[72:73], v[72:73]
	v_add_f32_e32 v1, v83, v1
	v_pk_fma_f32 v[74:75], v[74:75], v[8:9], v[86:87] op_sel_hi:[1,0,1] neg_lo:[0,0,1] neg_hi:[0,0,1]
	v_add_f32_e32 v1, v84, v1
	v_pk_mul_f32 v[86:87], v[74:75], v[74:75]
	v_add_f32_e32 v1, v85, v1
	v_pk_fma_f32 v[76:77], v[76:77], v[8:9], v[88:89] op_sel_hi:[1,0,1] neg_lo:[0,0,1] neg_hi:[0,0,1]
	v_add_f32_e32 v1, v86, v1
	v_pk_mul_f32 v[88:89], v[76:77], v[76:77]
	v_add_f32_e32 v1, v87, v1
	v_pk_fma_f32 v[78:79], v[78:79], v[8:9], v[90:91] op_sel_hi:[1,0,1] neg_lo:[0,0,1] neg_hi:[0,0,1]
	v_add_f32_e32 v1, v88, v1
	v_pk_mul_f32 v[90:91], v[78:79], v[78:79]
	v_add_f32_e32 v1, v89, v1
	v_pk_fma_f32 v[48:49], v[48:49], v[8:9], v[92:93] op_sel_hi:[1,0,1] neg_lo:[0,0,1] neg_hi:[0,0,1]
	v_add_f32_e32 v1, v90, v1
	v_pk_mul_f32 v[92:93], v[48:49], v[48:49]
	v_add_f32_e32 v1, v91, v1
	v_pk_fma_f32 v[50:51], v[50:51], v[8:9], v[94:95] op_sel_hi:[1,0,1] neg_lo:[0,0,1] neg_hi:[0,0,1]
	v_add_f32_e32 v1, v92, v1
	v_pk_mul_f32 v[94:95], v[50:51], v[50:51]
	v_add_f32_e32 v1, v93, v1
	v_pk_fma_f32 v[52:53], v[52:53], v[8:9], v[96:97] op_sel_hi:[1,0,1] neg_lo:[0,0,1] neg_hi:[0,0,1]
	v_add_f32_e32 v1, v94, v1
	v_pk_mul_f32 v[96:97], v[52:53], v[52:53]
	v_add_f32_e32 v1, v95, v1
	v_pk_fma_f32 v[54:55], v[54:55], v[8:9], v[98:99] op_sel_hi:[1,0,1] neg_lo:[0,0,1] neg_hi:[0,0,1]
	v_add_f32_e32 v1, v96, v1
	v_pk_mul_f32 v[98:99], v[54:55], v[54:55]
	v_add_f32_e32 v1, v97, v1
	v_pk_fma_f32 v[56:57], v[56:57], v[8:9], v[100:101] op_sel_hi:[1,0,1] neg_lo:[0,0,1] neg_hi:[0,0,1]
	v_add_f32_e32 v1, v98, v1
	v_pk_mul_f32 v[100:101], v[56:57], v[56:57]
	v_add_f32_e32 v1, v99, v1
	v_pk_fma_f32 v[58:59], v[58:59], v[8:9], v[102:103] op_sel_hi:[1,0,1] neg_lo:[0,0,1] neg_hi:[0,0,1]
	v_add_f32_e32 v1, v100, v1
	v_pk_mul_f32 v[102:103], v[58:59], v[58:59]
	v_add_f32_e32 v1, v101, v1
	v_pk_fma_f32 v[60:61], v[60:61], v[8:9], v[104:105] op_sel_hi:[1,0,1] neg_lo:[0,0,1] neg_hi:[0,0,1]
	v_add_f32_e32 v1, v102, v1
	v_pk_mul_f32 v[104:105], v[60:61], v[60:61]
	v_add_f32_e32 v1, v103, v1
	v_pk_fma_f32 v[62:63], v[62:63], v[8:9], v[106:107] op_sel_hi:[1,0,1] neg_lo:[0,0,1] neg_hi:[0,0,1]
	v_add_f32_e32 v1, v104, v1
	v_pk_mul_f32 v[106:107], v[62:63], v[62:63]
	v_add_f32_e32 v1, v105, v1
	v_pk_fma_f32 v[32:33], v[32:33], v[8:9], v[108:109] op_sel_hi:[1,0,1] neg_lo:[0,0,1] neg_hi:[0,0,1]
	v_add_f32_e32 v1, v106, v1
	v_pk_mul_f32 v[108:109], v[32:33], v[32:33]
	v_add_f32_e32 v1, v107, v1
	v_pk_fma_f32 v[34:35], v[34:35], v[8:9], v[110:111] op_sel_hi:[1,0,1] neg_lo:[0,0,1] neg_hi:[0,0,1]
	v_add_f32_e32 v1, v108, v1
	v_pk_mul_f32 v[110:111], v[34:35], v[34:35]
	v_add_f32_e32 v1, v109, v1
	v_pk_fma_f32 v[36:37], v[36:37], v[8:9], v[112:113] op_sel_hi:[1,0,1] neg_lo:[0,0,1] neg_hi:[0,0,1]
	v_add_f32_e32 v1, v110, v1
	v_pk_mul_f32 v[112:113], v[36:37], v[36:37]
	v_add_f32_e32 v1, v111, v1
	v_pk_fma_f32 v[38:39], v[38:39], v[8:9], v[114:115] op_sel_hi:[1,0,1] neg_lo:[0,0,1] neg_hi:[0,0,1]
	v_add_f32_e32 v1, v112, v1
	v_pk_mul_f32 v[114:115], v[38:39], v[38:39]
	v_add_f32_e32 v1, v113, v1
	v_pk_fma_f32 v[40:41], v[40:41], v[8:9], v[120:121] op_sel_hi:[1,0,1] neg_lo:[0,0,1] neg_hi:[0,0,1]
	v_add_f32_e32 v1, v114, v1
	v_pk_mul_f32 v[120:121], v[40:41], v[40:41]
	v_add_f32_e32 v1, v115, v1
	v_pk_fma_f32 v[42:43], v[42:43], v[8:9], v[122:123] op_sel_hi:[1,0,1] neg_lo:[0,0,1] neg_hi:[0,0,1]
	v_add_f32_e32 v1, v120, v1
	v_pk_mul_f32 v[122:123], v[42:43], v[42:43]
	v_add_f32_e32 v1, v121, v1
	v_pk_fma_f32 v[44:45], v[44:45], v[8:9], v[124:125] op_sel_hi:[1,0,1] neg_lo:[0,0,1] neg_hi:[0,0,1]
	v_add_f32_e32 v1, v122, v1
	v_pk_mul_f32 v[124:125], v[44:45], v[44:45]
	v_add_f32_e32 v1, v123, v1
	v_pk_fma_f32 v[46:47], v[46:47], v[8:9], v[126:127] op_sel_hi:[1,0,1] neg_lo:[0,0,1] neg_hi:[0,0,1]
	v_add_f32_e32 v1, v124, v1
	v_pk_mul_f32 v[126:127], v[46:47], v[46:47]
	v_add_f32_e32 v1, v125, v1
	s_waitcnt lgkmcnt(1)
	v_pk_fma_f32 v[128:129], v[16:17], v[8:9], v[128:129] op_sel_hi:[1,0,1] neg_lo:[0,0,1] neg_hi:[0,0,1]
	v_add_f32_e32 v1, v126, v1
	v_pk_mul_f32 v[16:17], v[128:129], v[128:129]
	v_add_f32_e32 v1, v127, v1
	v_pk_fma_f32 v[12:13], v[18:19], v[8:9], v[130:131] op_sel_hi:[1,0,1] neg_lo:[0,0,1] neg_hi:[0,0,1]
	v_add_f32_e32 v1, v16, v1
	v_pk_mul_f32 v[18:19], v[12:13], v[12:13]
	v_add_f32_e32 v1, v17, v1
	s_waitcnt lgkmcnt(0)
	v_pk_fma_f32 v[14:15], v[20:21], v[8:9], v[132:133] op_sel_hi:[1,0,1] neg_lo:[0,0,1] neg_hi:[0,0,1]
	v_add_f32_e32 v1, v18, v1
	v_pk_mul_f32 v[20:21], v[14:15], v[14:15]
	v_add_f32_e32 v1, v19, v1
	v_pk_fma_f32 v[10:11], v[22:23], v[8:9], v[134:135] op_sel_hi:[1,0,1] neg_lo:[0,0,1] neg_hi:[0,0,1]
	v_add_f32_e32 v1, v20, v1
	v_pk_mul_f32 v[22:23], v[10:11], v[10:11]
	v_add_f32_e32 v1, v21, v1
	v_pk_fma_f32 v[4:5], v[30:31], v[8:9], v[4:5] op_sel_hi:[1,0,1] neg_lo:[0,0,1] neg_hi:[0,0,1]
	v_pk_fma_f32 v[8:9], v[24:25], v[8:9], v[116:117] op_sel_hi:[1,0,1] neg_lo:[0,0,1] neg_hi:[0,0,1]
	v_add_f32_e32 v1, v22, v1
	v_pk_mul_f32 v[24:25], v[8:9], v[8:9]
	v_add_f32_e32 v1, v23, v1
	v_add_f32_e32 v1, v24, v1
	v_pk_mul_f32 v[118:119], v[6:7], v[6:7]
	v_add_f32_e32 v1, v25, v1
	v_add_f32_e32 v1, v118, v1
	v_pk_mul_f32 v[136:137], v[2:3], v[2:3]
	v_add_f32_e32 v1, v119, v1
	v_add_f32_e32 v1, v136, v1
	v_pk_mul_f32 v[30:31], v[4:5], v[4:5]
	v_add_f32_e32 v1, v137, v1
	v_add_f32_e32 v1, v30, v1
	v_add_f32_e32 v1, v31, v1
	ds_bpermute_b32 v16, v167, v1
	v_mov_b32_e32 v169, v0
	v_lshl_add_u64 v[20:21], v[170:171], 0, v[168:169]
	s_waitcnt lgkmcnt(0)
	v_add_f32_e32 v1, v1, v16
	v_fmamk_f32 v1, v1, 0x3c000000, v216
	v_rsq_f32_e32 v1, v1
	s_nop 0
	v_mul_f32_e32 v22, v145, v1
	v_pk_mul_f32 v[16:17], v[64:65], v[22:23] op_sel_hi:[1,0]
	v_pk_mul_f32 v[18:19], v[66:67], v[22:23] op_sel_hi:[1,0]
	global_load_dwordx4 v[80:83], v[152:153], off offset:32
	global_load_dwordx4 v[84:87], v[152:153], off offset:64
	global_load_dwordx4 v[88:91], v[152:153], off offset:96
	global_load_dwordx4 v[92:95], v[152:153], off offset:128
	global_load_dwordx4 v[96:99], v[152:153], off offset:160
	global_load_dwordx4 v[100:103], v[152:153], off offset:192
	global_load_dwordx4 v[104:107], v[152:153], off offset:224
	global_load_dwordx4 v[108:111], v[152:153], off offset:256
	global_load_dwordx4 v[112:115], v[152:153], off offset:288
	global_load_dwordx4 v[116:119], v[152:153], off offset:320
	global_load_dwordx4 v[120:123], v[152:153], off offset:352
	global_load_dwordx4 v[124:127], v[152:153], off offset:384
	global_load_dwordx4 v[132:135], v[152:153], off offset:416
	global_load_dwordx4 v[136:139], v[152:153], off offset:448
	global_load_dwordx4 v[140:143], v[152:153], off offset:480
	s_waitcnt vmcnt(0)
	v_pk_mul_f32 v[16:17], v[26:27], v[16:17]
	v_pk_mul_f32 v[18:19], v[28:29], v[18:19]
	v_cvt_pk_bf16_f32 v16, v16, v17
	v_cvt_pk_bf16_f32 v17, v18, v19
	global_store_dwordx2 v[20:21], v[16:17], off
	v_pk_mul_f32 v[24:25], v[68:69], v[22:23] op_sel_hi:[1,0]
	v_pk_mul_f32 v[26:27], v[70:71], v[22:23] op_sel_hi:[1,0]
	v_pk_mul_f32 v[12:13], v[12:13], v[22:23] op_sel_hi:[1,0]
	v_pk_mul_f32 v[10:11], v[10:11], v[22:23] op_sel_hi:[1,0]
	v_pk_mul_f32 v[8:9], v[8:9], v[22:23] op_sel_hi:[1,0]
	v_pk_mul_f32 v[6:7], v[6:7], v[22:23] op_sel_hi:[1,0]
	v_pk_mul_f32 v[2:3], v[2:3], v[22:23] op_sel_hi:[1,0]
	v_pk_mul_f32 v[4:5], v[4:5], v[22:23] op_sel_hi:[1,0]
	v_pk_mul_f32 v[16:17], v[80:81], v[24:25]
	v_pk_mul_f32 v[18:19], v[82:83], v[26:27]
	v_cvt_pk_bf16_f32 v16, v16, v17
	v_cvt_pk_bf16_f32 v17, v18, v19
	global_store_dwordx2 v[20:21], v[16:17], off offset:16
	v_pk_mul_f32 v[24:25], v[72:73], v[22:23] op_sel_hi:[1,0]
	v_pk_mul_f32 v[26:27], v[74:75], v[22:23] op_sel_hi:[1,0]
	v_pk_mul_f32 v[16:17], v[84:85], v[24:25]
	v_pk_mul_f32 v[18:19], v[86:87], v[26:27]
	v_cvt_pk_bf16_f32 v16, v16, v17
	v_cvt_pk_bf16_f32 v17, v18, v19
	global_store_dwordx2 v[20:21], v[16:17], off offset:32
	v_pk_mul_f32 v[24:25], v[76:77], v[22:23] op_sel_hi:[1,0]
	v_pk_mul_f32 v[26:27], v[78:79], v[22:23] op_sel_hi:[1,0]
	v_pk_mul_f32 v[16:17], v[88:89], v[24:25]
	v_pk_mul_f32 v[18:19], v[90:91], v[26:27]
	v_cvt_pk_bf16_f32 v16, v16, v17
	v_cvt_pk_bf16_f32 v17, v18, v19
	global_store_dwordx2 v[20:21], v[16:17], off offset:48
	v_pk_mul_f32 v[24:25], v[48:49], v[22:23] op_sel_hi:[1,0]
	v_pk_mul_f32 v[26:27], v[50:51], v[22:23] op_sel_hi:[1,0]
	v_pk_mul_f32 v[16:17], v[92:93], v[24:25]
	v_pk_mul_f32 v[18:19], v[94:95], v[26:27]
	v_cvt_pk_bf16_f32 v16, v16, v17
	v_cvt_pk_bf16_f32 v17, v18, v19
	global_store_dwordx2 v[20:21], v[16:17], off offset:64
	v_pk_mul_f32 v[24:25], v[52:53], v[22:23] op_sel_hi:[1,0]
	v_pk_mul_f32 v[26:27], v[54:55], v[22:23] op_sel_hi:[1,0]
	v_pk_mul_f32 v[16:17], v[96:97], v[24:25]
	v_pk_mul_f32 v[18:19], v[98:99], v[26:27]
	v_cvt_pk_bf16_f32 v16, v16, v17
	v_cvt_pk_bf16_f32 v17, v18, v19
	global_store_dwordx2 v[20:21], v[16:17], off offset:80
	v_pk_mul_f32 v[24:25], v[56:57], v[22:23] op_sel_hi:[1,0]
	v_pk_mul_f32 v[26:27], v[58:59], v[22:23] op_sel_hi:[1,0]
	v_pk_mul_f32 v[16:17], v[100:101], v[24:25]
	v_pk_mul_f32 v[18:19], v[102:103], v[26:27]
	v_cvt_pk_bf16_f32 v16, v16, v17
	v_cvt_pk_bf16_f32 v17, v18, v19
	global_store_dwordx2 v[20:21], v[16:17], off offset:96
	v_pk_mul_f32 v[24:25], v[60:61], v[22:23] op_sel_hi:[1,0]
	v_pk_mul_f32 v[26:27], v[62:63], v[22:23] op_sel_hi:[1,0]
	v_pk_mul_f32 v[16:17], v[104:105], v[24:25]
	v_pk_mul_f32 v[18:19], v[106:107], v[26:27]
	v_cvt_pk_bf16_f32 v16, v16, v17
	v_cvt_pk_bf16_f32 v17, v18, v19
	global_store_dwordx2 v[20:21], v[16:17], off offset:112
	v_pk_mul_f32 v[24:25], v[32:33], v[22:23] op_sel_hi:[1,0]
	v_pk_mul_f32 v[26:27], v[34:35], v[22:23] op_sel_hi:[1,0]
	v_pk_mul_f32 v[16:17], v[108:109], v[24:25]
	v_pk_mul_f32 v[18:19], v[110:111], v[26:27]
	v_cvt_pk_bf16_f32 v16, v16, v17
	v_cvt_pk_bf16_f32 v17, v18, v19
	global_store_dwordx2 v[20:21], v[16:17], off offset:128
	v_pk_mul_f32 v[24:25], v[36:37], v[22:23] op_sel_hi:[1,0]
	v_pk_mul_f32 v[26:27], v[38:39], v[22:23] op_sel_hi:[1,0]
	v_pk_mul_f32 v[16:17], v[112:113], v[24:25]
	v_pk_mul_f32 v[18:19], v[114:115], v[26:27]
	v_cvt_pk_bf16_f32 v16, v16, v17
	v_cvt_pk_bf16_f32 v17, v18, v19
	global_store_dwordx2 v[20:21], v[16:17], off offset:144
	v_pk_mul_f32 v[24:25], v[40:41], v[22:23] op_sel_hi:[1,0]
	v_pk_mul_f32 v[26:27], v[42:43], v[22:23] op_sel_hi:[1,0]
	v_pk_mul_f32 v[16:17], v[116:117], v[24:25]
	v_pk_mul_f32 v[18:19], v[118:119], v[26:27]
	v_cvt_pk_bf16_f32 v16, v16, v17
	v_cvt_pk_bf16_f32 v17, v18, v19
	global_store_dwordx2 v[20:21], v[16:17], off offset:160
	v_pk_mul_f32 v[24:25], v[44:45], v[22:23] op_sel_hi:[1,0]
	v_pk_mul_f32 v[26:27], v[46:47], v[22:23] op_sel_hi:[1,0]
	v_pk_mul_f32 v[16:17], v[120:121], v[24:25]
	v_pk_mul_f32 v[18:19], v[122:123], v[26:27]
	v_cvt_pk_bf16_f32 v16, v16, v17
	v_cvt_pk_bf16_f32 v17, v18, v19
	global_store_dwordx2 v[20:21], v[16:17], off offset:176
	v_pk_mul_f32 v[24:25], v[128:129], v[22:23] op_sel_hi:[1,0]
	v_pk_mul_f32 v[12:13], v[126:127], v[12:13]
	v_pk_mul_f32 v[16:17], v[124:125], v[24:25]
	s_nop 0
	v_cvt_pk_bf16_f32 v16, v16, v17
	v_cvt_pk_bf16_f32 v17, v12, v13
	global_store_dwordx2 v[20:21], v[16:17], off offset:192
	v_pk_mul_f32 v[12:13], v[14:15], v[22:23] op_sel_hi:[1,0]
	v_pk_mul_f32 v[10:11], v[134:135], v[10:11]
	v_pk_mul_f32 v[12:13], v[132:133], v[12:13]
	s_nop 0
	v_cvt_pk_bf16_f32 v12, v12, v13
	v_cvt_pk_bf16_f32 v13, v10, v11
	global_store_dwordx2 v[20:21], v[12:13], off offset:208
	v_pk_mul_f32 v[8:9], v[136:137], v[8:9]
	v_pk_mul_f32 v[6:7], v[138:139], v[6:7]
	v_cvt_pk_bf16_f32 v8, v8, v9
	v_cvt_pk_bf16_f32 v9, v6, v7
	global_store_dwordx2 v[20:21], v[8:9], off offset:224
	v_pk_mul_f32 v[2:3], v[140:141], v[2:3]
	v_pk_mul_f32 v[4:5], v[142:143], v[4:5]
	v_cvt_pk_bf16_f32 v2, v2, v3
	v_cvt_pk_bf16_f32 v3, v4, v5
	global_store_dwordx2 v[20:21], v[2:3], off offset:240

.LBB0_1306:
	s_cmpk_gt_u32 s0, 0xff
	s_waitcnt lgkmcnt(0)
	s_barrier
	s_cbranch_scc1 .LBB0_1308
	ds_read_b128 v[10:13], v1
	ds_read_b128 v[80:83], v1 offset:32
	ds_read_b128 v[84:87], v1 offset:64
	ds_read_b128 v[88:91], v1 offset:96
	ds_read_b128 v[92:95], v1 offset:128
	ds_read_b128 v[96:99], v1 offset:160
	ds_read_b128 v[100:103], v1 offset:192
	ds_read_b128 v[104:107], v1 offset:224
	ds_read_b128 v[108:111], v1 offset:256
	ds_read_b128 v[112:115], v1 offset:288
	ds_read_b128 v[116:119], v1 offset:448
	ds_read_b128 v[120:123], v1 offset:320
	ds_read_b128 v[124:127], v1 offset:352
	ds_read_b128 v[2:5], v1 offset:480
	s_waitcnt vmcnt(3)
	ds_read_b128 v[128:131], v1 offset:384
	s_waitcnt vmcnt(2)
	ds_read_b128 v[132:135], v1 offset:416
	s_waitcnt lgkmcnt(5)
	v_pk_fma_f32 v[6:7], v[26:27], v[8:9], v[118:119] op_sel_hi:[1,0,1] neg_lo:[0,0,1] neg_hi:[0,0,1]
	v_pk_fma_f32 v[64:65], v[64:65], v[8:9], v[10:11] op_sel_hi:[1,0,1] neg_lo:[0,0,1] neg_hi:[0,0,1]
	s_waitcnt lgkmcnt(2)
	v_pk_fma_f32 v[2:3], v[28:29], v[8:9], v[2:3] op_sel_hi:[1,0,1] neg_lo:[0,0,1] neg_hi:[0,0,1]
	global_load_dwordx4 v[26:29], v[152:153], off offset:512
	v_pk_fma_f32 v[66:67], v[66:67], v[8:9], v[12:13] op_sel_hi:[1,0,1] neg_lo:[0,0,1] neg_hi:[0,0,1]
	s_waitcnt vmcnt(1)
	v_pk_mul_f32 v[140:141], v[64:65], v[64:65]
	v_pk_mul_f32 v[138:139], v[66:67], v[66:67]
	v_add_f32_e32 v1, v140, v141
	v_pk_fma_f32 v[68:69], v[68:69], v[8:9], v[80:81] op_sel_hi:[1,0,1] neg_lo:[0,0,1] neg_hi:[0,0,1]
	v_add_f32_e32 v1, v138, v1
	v_pk_mul_f32 v[80:81], v[68:69], v[68:69]
	v_add_f32_e32 v1, v139, v1
	v_pk_fma_f32 v[70:71], v[70:71], v[8:9], v[82:83] op_sel_hi:[1,0,1] neg_lo:[0,0,1] neg_hi:[0,0,1]
	v_add_f32_e32 v1, v80, v1
	v_pk_mul_f32 v[82:83], v[70:71], v[70:71]
	v_add_f32_e32 v1, v81, v1
	v_pk_fma_f32 v[72:73], v[72:73], v[8:9], v[84:85] op_sel_hi:[1,0,1] neg_lo:[0,0,1] neg_hi:[0,0,1]
	v_add_f32_e32 v1, v82, v1
	v_pk_mul_f32 v[84:85], v[72:73], v[72:73]
	v_add_f32_e32 v1, v83, v1
	v_pk_fma_f32 v[74:75], v[74:75], v[8:9], v[86:87] op_sel_hi:[1,0,1] neg_lo:[0,0,1] neg_hi:[0,0,1]
	v_add_f32_e32 v1, v84, v1
	v_pk_mul_f32 v[86:87], v[74:75], v[74:75]
	v_add_f32_e32 v1, v85, v1
	v_pk_fma_f32 v[76:77], v[76:77], v[8:9], v[88:89] op_sel_hi:[1,0,1] neg_lo:[0,0,1] neg_hi:[0,0,1]
	v_add_f32_e32 v1, v86, v1
	v_pk_mul_f32 v[88:89], v[76:77], v[76:77]
	v_add_f32_e32 v1, v87, v1
	v_pk_fma_f32 v[78:79], v[78:79], v[8:9], v[90:91] op_sel_hi:[1,0,1] neg_lo:[0,0,1] neg_hi:[0,0,1]
	v_add_f32_e32 v1, v88, v1
	v_pk_mul_f32 v[90:91], v[78:79], v[78:79]
	v_add_f32_e32 v1, v89, v1
	v_pk_fma_f32 v[48:49], v[48:49], v[8:9], v[92:93] op_sel_hi:[1,0,1] neg_lo:[0,0,1] neg_hi:[0,0,1]
	v_add_f32_e32 v1, v90, v1
	v_pk_mul_f32 v[92:93], v[48:49], v[48:49]
	v_add_f32_e32 v1, v91, v1
	v_pk_fma_f32 v[50:51], v[50:51], v[8:9], v[94:95] op_sel_hi:[1,0,1] neg_lo:[0,0,1] neg_hi:[0,0,1]
	v_add_f32_e32 v1, v92, v1
	v_pk_mul_f32 v[94:95], v[50:51], v[50:51]
	v_add_f32_e32 v1, v93, v1
	v_pk_fma_f32 v[52:53], v[52:53], v[8:9], v[96:97] op_sel_hi:[1,0,1] neg_lo:[0,0,1] neg_hi:[0,0,1]
	v_add_f32_e32 v1, v94, v1
	v_pk_mul_f32 v[96:97], v[52:53], v[52:53]
	v_add_f32_e32 v1, v95, v1
	v_pk_fma_f32 v[54:55], v[54:55], v[8:9], v[98:99] op_sel_hi:[1,0,1] neg_lo:[0,0,1] neg_hi:[0,0,1]
	v_add_f32_e32 v1, v96, v1
	v_pk_mul_f32 v[98:99], v[54:55], v[54:55]
	v_add_f32_e32 v1, v97, v1
	v_pk_fma_f32 v[56:57], v[56:57], v[8:9], v[100:101] op_sel_hi:[1,0,1] neg_lo:[0,0,1] neg_hi:[0,0,1]
	v_add_f32_e32 v1, v98, v1
	v_pk_mul_f32 v[100:101], v[56:57], v[56:57]
	v_add_f32_e32 v1, v99, v1
	v_pk_fma_f32 v[58:59], v[58:59], v[8:9], v[102:103] op_sel_hi:[1,0,1] neg_lo:[0,0,1] neg_hi:[0,0,1]
	v_add_f32_e32 v1, v100, v1
	v_pk_mul_f32 v[102:103], v[58:59], v[58:59]
	v_add_f32_e32 v1, v101, v1
	v_pk_fma_f32 v[60:61], v[60:61], v[8:9], v[104:105] op_sel_hi:[1,0,1] neg_lo:[0,0,1] neg_hi:[0,0,1]
	v_add_f32_e32 v1, v102, v1
	v_pk_mul_f32 v[104:105], v[60:61], v[60:61]
	v_add_f32_e32 v1, v103, v1
	v_pk_fma_f32 v[62:63], v[62:63], v[8:9], v[106:107] op_sel_hi:[1,0,1] neg_lo:[0,0,1] neg_hi:[0,0,1]
	v_add_f32_e32 v1, v104, v1
	v_pk_mul_f32 v[106:107], v[62:63], v[62:63]
	v_add_f32_e32 v1, v105, v1
	v_pk_fma_f32 v[32:33], v[32:33], v[8:9], v[108:109] op_sel_hi:[1,0,1] neg_lo:[0,0,1] neg_hi:[0,0,1]
	v_add_f32_e32 v1, v106, v1
	v_pk_mul_f32 v[108:109], v[32:33], v[32:33]
	v_add_f32_e32 v1, v107, v1
	v_pk_fma_f32 v[34:35], v[34:35], v[8:9], v[110:111] op_sel_hi:[1,0,1] neg_lo:[0,0,1] neg_hi:[0,0,1]
	v_add_f32_e32 v1, v108, v1
	v_pk_mul_f32 v[110:111], v[34:35], v[34:35]
	v_add_f32_e32 v1, v109, v1
	v_pk_fma_f32 v[36:37], v[36:37], v[8:9], v[112:113] op_sel_hi:[1,0,1] neg_lo:[0,0,1] neg_hi:[0,0,1]
	v_add_f32_e32 v1, v110, v1
	v_pk_mul_f32 v[112:113], v[36:37], v[36:37]
	v_add_f32_e32 v1, v111, v1
	v_pk_fma_f32 v[38:39], v[38:39], v[8:9], v[114:115] op_sel_hi:[1,0,1] neg_lo:[0,0,1] neg_hi:[0,0,1]
	v_add_f32_e32 v1, v112, v1
	v_pk_mul_f32 v[114:115], v[38:39], v[38:39]
	v_add_f32_e32 v1, v113, v1
	v_pk_fma_f32 v[40:41], v[40:41], v[8:9], v[120:121] op_sel_hi:[1,0,1] neg_lo:[0,0,1] neg_hi:[0,0,1]
	v_add_f32_e32 v1, v114, v1
	v_pk_mul_f32 v[120:121], v[40:41], v[40:41]
	v_add_f32_e32 v1, v115, v1
	v_pk_fma_f32 v[42:43], v[42:43], v[8:9], v[122:123] op_sel_hi:[1,0,1] neg_lo:[0,0,1] neg_hi:[0,0,1]
	v_add_f32_e32 v1, v120, v1
	v_pk_mul_f32 v[122:123], v[42:43], v[42:43]
	v_add_f32_e32 v1, v121, v1
	v_pk_fma_f32 v[44:45], v[44:45], v[8:9], v[124:125] op_sel_hi:[1,0,1] neg_lo:[0,0,1] neg_hi:[0,0,1]
	v_add_f32_e32 v1, v122, v1
	v_pk_mul_f32 v[124:125], v[44:45], v[44:45]
	v_add_f32_e32 v1, v123, v1
	v_pk_fma_f32 v[46:47], v[46:47], v[8:9], v[126:127] op_sel_hi:[1,0,1] neg_lo:[0,0,1] neg_hi:[0,0,1]
	v_add_f32_e32 v1, v124, v1
	v_pk_mul_f32 v[126:127], v[46:47], v[46:47]
	v_add_f32_e32 v1, v125, v1
	s_waitcnt lgkmcnt(1)
	v_pk_fma_f32 v[128:129], v[16:17], v[8:9], v[128:129] op_sel_hi:[1,0,1] neg_lo:[0,0,1] neg_hi:[0,0,1]
	v_add_f32_e32 v1, v126, v1
	v_pk_mul_f32 v[16:17], v[128:129], v[128:129]
	v_add_f32_e32 v1, v127, v1
	v_pk_fma_f32 v[12:13], v[18:19], v[8:9], v[130:131] op_sel_hi:[1,0,1] neg_lo:[0,0,1] neg_hi:[0,0,1]
	v_add_f32_e32 v1, v16, v1
	v_pk_mul_f32 v[18:19], v[12:13], v[12:13]
	v_add_f32_e32 v1, v17, v1
	s_waitcnt lgkmcnt(0)
	v_pk_fma_f32 v[14:15], v[20:21], v[8:9], v[132:133] op_sel_hi:[1,0,1] neg_lo:[0,0,1] neg_hi:[0,0,1]
	v_add_f32_e32 v1, v18, v1
	v_pk_mul_f32 v[20:21], v[14:15], v[14:15]
	v_add_f32_e32 v1, v19, v1
	v_pk_fma_f32 v[10:11], v[22:23], v[8:9], v[134:135] op_sel_hi:[1,0,1] neg_lo:[0,0,1] neg_hi:[0,0,1]
	v_add_f32_e32 v1, v20, v1
	v_pk_mul_f32 v[22:23], v[10:11], v[10:11]
	v_add_f32_e32 v1, v21, v1
	v_pk_fma_f32 v[4:5], v[30:31], v[8:9], v[4:5] op_sel_hi:[1,0,1] neg_lo:[0,0,1] neg_hi:[0,0,1]
	v_pk_fma_f32 v[8:9], v[24:25], v[8:9], v[116:117] op_sel_hi:[1,0,1] neg_lo:[0,0,1] neg_hi:[0,0,1]
	v_add_f32_e32 v1, v22, v1
	v_pk_mul_f32 v[24:25], v[8:9], v[8:9]
	v_add_f32_e32 v1, v23, v1
	v_add_f32_e32 v1, v24, v1
	v_pk_mul_f32 v[118:119], v[6:7], v[6:7]
	v_add_f32_e32 v1, v25, v1
	v_add_f32_e32 v1, v118, v1
	v_pk_mul_f32 v[136:137], v[2:3], v[2:3]
	v_add_f32_e32 v1, v119, v1
	v_add_f32_e32 v1, v136, v1
	v_pk_mul_f32 v[30:31], v[4:5], v[4:5]
	v_add_f32_e32 v1, v137, v1
	v_add_f32_e32 v1, v30, v1
	v_add_f32_e32 v1, v31, v1
	ds_bpermute_b32 v16, v167, v1
	v_mov_b32_e32 v169, v0
	v_lshl_add_u64 v[20:21], v[170:171], 0, v[168:169]
	s_waitcnt lgkmcnt(0)
	v_add_f32_e32 v1, v1, v16
	v_fmamk_f32 v1, v1, 0x3c000000, v218
	v_rsq_f32_e32 v1, v1
	s_nop 0
	v_mul_f32_e32 v22, v145, v1
	v_pk_mul_f32 v[16:17], v[64:65], v[22:23] op_sel_hi:[1,0]
	v_pk_mul_f32 v[18:19], v[66:67], v[22:23] op_sel_hi:[1,0]
	global_load_dwordx4 v[80:83], v[152:153], off offset:544
	global_load_dwordx4 v[84:87], v[152:153], off offset:576
	global_load_dwordx4 v[88:91], v[152:153], off offset:608
	global_load_dwordx4 v[92:95], v[152:153], off offset:640
	global_load_dwordx4 v[96:99], v[152:153], off offset:672
	global_load_dwordx4 v[100:103], v[152:153], off offset:704
	global_load_dwordx4 v[104:107], v[152:153], off offset:736
	global_load_dwordx4 v[108:111], v[152:153], off offset:768
	global_load_dwordx4 v[112:115], v[152:153], off offset:800
	global_load_dwordx4 v[116:119], v[152:153], off offset:832
	global_load_dwordx4 v[120:123], v[152:153], off offset:864
	global_load_dwordx4 v[124:127], v[152:153], off offset:896
	global_load_dwordx4 v[132:135], v[152:153], off offset:928
	global_load_dwordx4 v[136:139], v[152:153], off offset:960
	global_load_dwordx4 v[140:143], v[152:153], off offset:992
	s_waitcnt vmcnt(0)
	v_pk_mul_f32 v[16:17], v[26:27], v[16:17]
	v_pk_mul_f32 v[18:19], v[28:29], v[18:19]
	v_cvt_pk_bf16_f32 v16, v16, v17
	v_cvt_pk_bf16_f32 v17, v18, v19
	global_store_dwordx2 v[20:21], v[16:17], off
	v_pk_mul_f32 v[24:25], v[68:69], v[22:23] op_sel_hi:[1,0]
	v_pk_mul_f32 v[26:27], v[70:71], v[22:23] op_sel_hi:[1,0]
	v_pk_mul_f32 v[12:13], v[12:13], v[22:23] op_sel_hi:[1,0]
	v_pk_mul_f32 v[10:11], v[10:11], v[22:23] op_sel_hi:[1,0]
	v_pk_mul_f32 v[8:9], v[8:9], v[22:23] op_sel_hi:[1,0]
	v_pk_mul_f32 v[6:7], v[6:7], v[22:23] op_sel_hi:[1,0]
	v_pk_mul_f32 v[2:3], v[2:3], v[22:23] op_sel_hi:[1,0]
	v_pk_mul_f32 v[4:5], v[4:5], v[22:23] op_sel_hi:[1,0]
	v_pk_mul_f32 v[16:17], v[80:81], v[24:25]
	v_pk_mul_f32 v[18:19], v[82:83], v[26:27]
	v_cvt_pk_bf16_f32 v16, v16, v17
	v_cvt_pk_bf16_f32 v17, v18, v19
	global_store_dwordx2 v[20:21], v[16:17], off offset:16
	v_pk_mul_f32 v[24:25], v[72:73], v[22:23] op_sel_hi:[1,0]
	v_pk_mul_f32 v[26:27], v[74:75], v[22:23] op_sel_hi:[1,0]
	v_pk_mul_f32 v[16:17], v[84:85], v[24:25]
	v_pk_mul_f32 v[18:19], v[86:87], v[26:27]
	v_cvt_pk_bf16_f32 v16, v16, v17
	v_cvt_pk_bf16_f32 v17, v18, v19
	global_store_dwordx2 v[20:21], v[16:17], off offset:32
	v_pk_mul_f32 v[24:25], v[76:77], v[22:23] op_sel_hi:[1,0]
	v_pk_mul_f32 v[26:27], v[78:79], v[22:23] op_sel_hi:[1,0]
	v_pk_mul_f32 v[16:17], v[88:89], v[24:25]
	v_pk_mul_f32 v[18:19], v[90:91], v[26:27]
	v_cvt_pk_bf16_f32 v16, v16, v17
	v_cvt_pk_bf16_f32 v17, v18, v19
	global_store_dwordx2 v[20:21], v[16:17], off offset:48
	v_pk_mul_f32 v[24:25], v[48:49], v[22:23] op_sel_hi:[1,0]
	v_pk_mul_f32 v[26:27], v[50:51], v[22:23] op_sel_hi:[1,0]
	v_pk_mul_f32 v[16:17], v[92:93], v[24:25]
	v_pk_mul_f32 v[18:19], v[94:95], v[26:27]
	v_cvt_pk_bf16_f32 v16, v16, v17
	v_cvt_pk_bf16_f32 v17, v18, v19
	global_store_dwordx2 v[20:21], v[16:17], off offset:64
	v_pk_mul_f32 v[24:25], v[52:53], v[22:23] op_sel_hi:[1,0]
	v_pk_mul_f32 v[26:27], v[54:55], v[22:23] op_sel_hi:[1,0]
	v_pk_mul_f32 v[16:17], v[96:97], v[24:25]
	v_pk_mul_f32 v[18:19], v[98:99], v[26:27]
	v_cvt_pk_bf16_f32 v16, v16, v17
	v_cvt_pk_bf16_f32 v17, v18, v19
	global_store_dwordx2 v[20:21], v[16:17], off offset:80
	v_pk_mul_f32 v[24:25], v[56:57], v[22:23] op_sel_hi:[1,0]
	v_pk_mul_f32 v[26:27], v[58:59], v[22:23] op_sel_hi:[1,0]
	v_pk_mul_f32 v[16:17], v[100:101], v[24:25]
	v_pk_mul_f32 v[18:19], v[102:103], v[26:27]
	v_cvt_pk_bf16_f32 v16, v16, v17
	v_cvt_pk_bf16_f32 v17, v18, v19
	global_store_dwordx2 v[20:21], v[16:17], off offset:96
	v_pk_mul_f32 v[24:25], v[60:61], v[22:23] op_sel_hi:[1,0]
	v_pk_mul_f32 v[26:27], v[62:63], v[22:23] op_sel_hi:[1,0]
	v_pk_mul_f32 v[16:17], v[104:105], v[24:25]
	v_pk_mul_f32 v[18:19], v[106:107], v[26:27]
	v_cvt_pk_bf16_f32 v16, v16, v17
	v_cvt_pk_bf16_f32 v17, v18, v19
	global_store_dwordx2 v[20:21], v[16:17], off offset:112
	v_pk_mul_f32 v[24:25], v[32:33], v[22:23] op_sel_hi:[1,0]
	v_pk_mul_f32 v[26:27], v[34:35], v[22:23] op_sel_hi:[1,0]
	v_pk_mul_f32 v[16:17], v[108:109], v[24:25]
	v_pk_mul_f32 v[18:19], v[110:111], v[26:27]
	v_cvt_pk_bf16_f32 v16, v16, v17
	v_cvt_pk_bf16_f32 v17, v18, v19
	global_store_dwordx2 v[20:21], v[16:17], off offset:128
	v_pk_mul_f32 v[24:25], v[36:37], v[22:23] op_sel_hi:[1,0]
	v_pk_mul_f32 v[26:27], v[38:39], v[22:23] op_sel_hi:[1,0]
	v_pk_mul_f32 v[16:17], v[112:113], v[24:25]
	v_pk_mul_f32 v[18:19], v[114:115], v[26:27]
	v_cvt_pk_bf16_f32 v16, v16, v17
	v_cvt_pk_bf16_f32 v17, v18, v19
	global_store_dwordx2 v[20:21], v[16:17], off offset:144
	v_pk_mul_f32 v[24:25], v[40:41], v[22:23] op_sel_hi:[1,0]
	v_pk_mul_f32 v[26:27], v[42:43], v[22:23] op_sel_hi:[1,0]
	v_pk_mul_f32 v[16:17], v[116:117], v[24:25]
	v_pk_mul_f32 v[18:19], v[118:119], v[26:27]
	v_cvt_pk_bf16_f32 v16, v16, v17
	v_cvt_pk_bf16_f32 v17, v18, v19
	global_store_dwordx2 v[20:21], v[16:17], off offset:160
	v_pk_mul_f32 v[24:25], v[44:45], v[22:23] op_sel_hi:[1,0]
	v_pk_mul_f32 v[26:27], v[46:47], v[22:23] op_sel_hi:[1,0]
	v_pk_mul_f32 v[16:17], v[120:121], v[24:25]
	v_pk_mul_f32 v[18:19], v[122:123], v[26:27]
	v_cvt_pk_bf16_f32 v16, v16, v17
	v_cvt_pk_bf16_f32 v17, v18, v19
	global_store_dwordx2 v[20:21], v[16:17], off offset:176
	v_pk_mul_f32 v[24:25], v[128:129], v[22:23] op_sel_hi:[1,0]
	v_pk_mul_f32 v[12:13], v[126:127], v[12:13]
	v_pk_mul_f32 v[16:17], v[124:125], v[24:25]
	s_nop 0
	v_cvt_pk_bf16_f32 v16, v16, v17
	v_cvt_pk_bf16_f32 v17, v12, v13
	global_store_dwordx2 v[20:21], v[16:17], off offset:192
	v_pk_mul_f32 v[12:13], v[14:15], v[22:23] op_sel_hi:[1,0]
	v_pk_mul_f32 v[10:11], v[134:135], v[10:11]
	v_pk_mul_f32 v[12:13], v[132:133], v[12:13]
	s_nop 0
	v_cvt_pk_bf16_f32 v12, v12, v13
	v_cvt_pk_bf16_f32 v13, v10, v11
	global_store_dwordx2 v[20:21], v[12:13], off offset:208
	v_pk_mul_f32 v[8:9], v[136:137], v[8:9]
	v_pk_mul_f32 v[6:7], v[138:139], v[6:7]
	v_cvt_pk_bf16_f32 v8, v8, v9
	v_cvt_pk_bf16_f32 v9, v6, v7
	global_store_dwordx2 v[20:21], v[8:9], off offset:224
	v_pk_mul_f32 v[2:3], v[140:141], v[2:3]
	v_pk_mul_f32 v[4:5], v[142:143], v[4:5]
	v_cvt_pk_bf16_f32 v2, v2, v3
	v_cvt_pk_bf16_f32 v3, v4, v5
	global_store_dwordx2 v[20:21], v[2:3], off offset:240
